# v28 + non-temporal (nt) loads and stores in the moved W_up transposes so they do not evict GEMM1 output from cache
# speedup vs baseline: 1.0084x; 1.0084x over previous
.LBB0_268:
	s_cmpk_lg_i32 s96, 0x100
	s_cbranch_scc1 .Ltup_skip
	s_cmpk_lt_u32 s76, 0x7b
	s_cbranch_scc1 .Ltup_skip
	s_cmpk_gt_u32 s76, 0xef
	s_cbranch_scc1 .Ltup_skip
	v_readlane_b32 s2, v237, 42
	v_readlane_b32 s3, v237, 43
	v_readlane_b32 s4, v237, 40
	v_readlane_b32 s5, v237, 41
	s_add_u32 s40, s92, 0x3000000
	s_addc_u32 s41, s93, 0
	v_and_b32_e32 v83, 31, v172
	v_lshrrev_b32_e32 v84, 5, v172
	v_mul_u32_u24_e32 v66, 0x58000, v84
	v_lshl_add_u32 v66, v83, 4, v66
	v_add_u32_e32 v67, 0xb000, v66
	v_add_u32_e32 v68, 0x16000, v66
	v_add_u32_e32 v69, 0x21000, v66
	v_add_u32_e32 v70, 0x2c000, v66
	v_add_u32_e32 v71, 0x37000, v66
	v_add_u32_e32 v72, 0x42000, v66
	v_add_u32_e32 v73, 0x4d000, v66
	v_lshlrev_b32_e32 v74, 5, v84
	v_and_b32_e32 v85, 15, v83
	v_xor_b32_e32 v85, v85, v84
	v_lshlrev_b32_e32 v85, 4, v85
	v_lshl_add_u32 v75, v83, 10, v85
	v_lshrrev_b32_e32 v83, 4, v172
	v_and_b32_e32 v84, 15, v172
	v_lshrrev_b32_e32 v85, 6, v172
	v_xor_b32_e32 v85, v85, v84
	v_lshlrev_b32_e32 v85, 4, v85
	v_lshl_add_u32 v76, v83, 8, v85
	v_xor_b32_e32 v77, 0x80, v76
	v_lshlrev_b32_e32 v84, 4, v84
	v_lshl_add_u32 v79, v83, 12, v84
	v_add_u32_e32 v80, 0x20000, v79
	v_add_u32_e32 v81, 0x40000, v79
	v_add_u32_e32 v82, 0x60000, v79
	s_add_i32 s9, s76, 0xffffff8f
	s_mul_i32 s12, s9, 0xba2f
	s_lshr_b32 s12, s12, 22
	s_mul_i32 s57, s12, 0x58
	s_sub_i32 s42, s9, s57
	s_mul_i32 s57, s12, 0x580000
	s_lshl_b32 s58, s42, 9
	s_add_i32 s57, s57, s58
	s_add_u32 s52, s2, s57
	s_addc_u32 s53, s3, 0
	s_lshl_b32 s58, s12, 9
	s_add_u32 s54, s4, s58
	s_addc_u32 s55, s5, 0
	s_cmp_gt_u32 s42, 43
	s_cselect_b32 s58, 0x80000, 0
	s_cselect_b32 s57, 44, 0
	s_sub_i32 s57, s42, s57
	s_lshl_b32 s57, s57, 20
	s_add_i32 s57, s57, s58
	s_lshl_b32 s58, s12, 8
	s_add_i32 s57, s57, s58
	s_add_u32 s60, s40, s57
	s_addc_u32 s61, s41, 0
	s_add_i32 s9, s9, 0x75
	s_nop 0
	global_load_dwordx4 v[206:209], v74, s[54:55] offset:0
	global_load_dwordx4 v[210:213], v74, s[54:55] offset:16
	global_load_dwordx4 v[174:177], v66, s[52:53] nt
	global_load_dwordx4 v[178:181], v67, s[52:53] nt
	global_load_dwordx4 v[182:185], v68, s[52:53] nt
	global_load_dwordx4 v[186:189], v69, s[52:53] nt
	global_load_dwordx4 v[190:193], v70, s[52:53] nt
	global_load_dwordx4 v[194:197], v71, s[52:53] nt
	global_load_dwordx4 v[198:201], v72, s[52:53] nt
	global_load_dwordx4 v[202:205], v73, s[52:53] nt
	s_mul_i32 s12, s9, 0xba2f
	s_lshr_b32 s12, s12, 22
	s_mul_i32 s57, s12, 0x58
	s_sub_i32 s42, s9, s57
	s_mul_i32 s57, s12, 0x580000
	s_lshl_b32 s58, s42, 9
	s_add_i32 s57, s57, s58
	s_add_u32 s62, s2, s57
	s_addc_u32 s63, s3, 0
	s_lshl_b32 s58, s12, 9
	s_add_u32 s64, s4, s58
	s_addc_u32 s65, s5, 0
	s_cmp_gt_u32 s42, 43
	s_cselect_b32 s58, 0x80000, 0
	s_cselect_b32 s57, 44, 0
	s_sub_i32 s57, s42, s57
	s_lshl_b32 s57, s57, 20
	s_add_i32 s57, s57, s58
	s_lshl_b32 s58, s12, 8
	s_add_i32 s57, s57, s58
	s_add_u32 s66, s40, s57
	s_addc_u32 s67, s41, 0
	s_add_i32 s9, s9, 0x75
	s_nop 0
	global_load_dwordx4 v[162:165], v74, s[64:65] offset:0
	global_load_dwordx4 v[166:169], v74, s[64:65] offset:16
	global_load_dwordx4 v[130:133], v66, s[62:63] nt
	global_load_dwordx4 v[134:137], v67, s[62:63] nt
	global_load_dwordx4 v[138:141], v68, s[62:63] nt
	global_load_dwordx4 v[142:145], v69, s[62:63] nt
	global_load_dwordx4 v[146:149], v70, s[62:63] nt
	global_load_dwordx4 v[150:153], v71, s[62:63] nt
	global_load_dwordx4 v[154:157], v72, s[62:63] nt
	global_load_dwordx4 v[158:161], v73, s[62:63] nt
	s_waitcnt vmcnt(10)
	v_mul_f32_e32 v174, v174, v206
	v_mul_f32_e32 v175, v175, v206
	v_mul_f32_e32 v176, v176, v206
	v_mul_f32_e32 v177, v177, v206
	v_mul_f32_e32 v178, v178, v207
	v_mul_f32_e32 v179, v179, v207
	v_mul_f32_e32 v180, v180, v207
	v_mul_f32_e32 v181, v181, v207
	v_mul_f32_e32 v182, v182, v208
	v_mul_f32_e32 v183, v183, v208
	v_mul_f32_e32 v184, v184, v208
	v_mul_f32_e32 v185, v185, v208
	v_mul_f32_e32 v186, v186, v209
	v_mul_f32_e32 v187, v187, v209
	v_mul_f32_e32 v188, v188, v209
	v_mul_f32_e32 v189, v189, v209
	v_mul_f32_e32 v190, v190, v210
	v_mul_f32_e32 v191, v191, v210
	v_mul_f32_e32 v192, v192, v210
	v_mul_f32_e32 v193, v193, v210
	v_mul_f32_e32 v194, v194, v211
	v_mul_f32_e32 v195, v195, v211
	v_mul_f32_e32 v196, v196, v211
	v_mul_f32_e32 v197, v197, v211
	v_mul_f32_e32 v198, v198, v212
	v_mul_f32_e32 v199, v199, v212
	v_mul_f32_e32 v200, v200, v212
	v_mul_f32_e32 v201, v201, v212
	v_mul_f32_e32 v202, v202, v213
	v_mul_f32_e32 v203, v203, v213
	v_mul_f32_e32 v204, v204, v213
	v_mul_f32_e32 v205, v205, v213
	v_cvt_pk_bf16_f32 v214, v174, v178
	v_cvt_pk_bf16_f32 v215, v182, v186
	v_cvt_pk_bf16_f32 v216, v190, v194
	v_cvt_pk_bf16_f32 v217, v198, v202
	v_cvt_pk_bf16_f32 v218, v175, v179
	v_cvt_pk_bf16_f32 v219, v183, v187
	v_cvt_pk_bf16_f32 v220, v191, v195
	v_cvt_pk_bf16_f32 v221, v199, v203
	v_cvt_pk_bf16_f32 v222, v176, v180
	v_cvt_pk_bf16_f32 v223, v184, v188
	v_cvt_pk_bf16_f32 v224, v192, v196
	v_cvt_pk_bf16_f32 v225, v200, v204
	v_cvt_pk_bf16_f32 v226, v177, v181
	v_cvt_pk_bf16_f32 v227, v185, v189
	v_cvt_pk_bf16_f32 v228, v193, v197
	v_cvt_pk_bf16_f32 v229, v201, v205
	ds_write_b128 v75, v[214:217] offset:0
	ds_write_b128 v75, v[218:221] offset:256
	ds_write_b128 v75, v[222:225] offset:512
	ds_write_b128 v75, v[226:229] offset:768
	s_mov_b64 s[68:69], s[60:61]
	s_mul_i32 s12, s9, 0xba2f
	s_lshr_b32 s12, s12, 22
	s_mul_i32 s57, s12, 0x58
	s_sub_i32 s42, s9, s57
	s_mul_i32 s57, s12, 0x580000
	s_lshl_b32 s58, s42, 9
	s_add_i32 s57, s57, s58
	s_add_u32 s52, s2, s57
	s_addc_u32 s53, s3, 0
	s_lshl_b32 s58, s12, 9
	s_add_u32 s54, s4, s58
	s_addc_u32 s55, s5, 0
	s_cmp_gt_u32 s42, 43
	s_cselect_b32 s58, 0x80000, 0
	s_cselect_b32 s57, 44, 0
	s_sub_i32 s57, s42, s57
	s_lshl_b32 s57, s57, 20
	s_add_i32 s57, s57, s58
	s_lshl_b32 s58, s12, 8
	s_add_i32 s57, s57, s58
	s_add_u32 s60, s40, s57
	s_addc_u32 s61, s41, 0
	s_add_i32 s9, s9, 0x75
	s_nop 0
	global_load_dwordx4 v[206:209], v74, s[54:55] offset:0
	global_load_dwordx4 v[210:213], v74, s[54:55] offset:16
	global_load_dwordx4 v[174:177], v66, s[52:53] nt
	global_load_dwordx4 v[178:181], v67, s[52:53] nt
	global_load_dwordx4 v[182:185], v68, s[52:53] nt
	global_load_dwordx4 v[186:189], v69, s[52:53] nt
	global_load_dwordx4 v[190:193], v70, s[52:53] nt
	global_load_dwordx4 v[194:197], v71, s[52:53] nt
	global_load_dwordx4 v[198:201], v72, s[52:53] nt
	global_load_dwordx4 v[202:205], v73, s[52:53] nt
	s_waitcnt lgkmcnt(0)
	s_barrier
	ds_read_b128 v[50:53], v76 offset:0
	ds_read_b128 v[54:57], v77 offset:8192
	ds_read_b128 v[58:61], v76 offset:16384
	ds_read_b128 v[62:65], v77 offset:24576
	s_waitcnt lgkmcnt(3)
	global_store_dwordx4 v79, v[50:53], s[68:69] nt
	s_waitcnt lgkmcnt(2)
	global_store_dwordx4 v80, v[54:57], s[68:69] nt
	s_waitcnt lgkmcnt(1)
	global_store_dwordx4 v81, v[58:61], s[68:69] nt
	s_waitcnt lgkmcnt(0)
	global_store_dwordx4 v82, v[62:65], s[68:69] nt
	s_waitcnt vmcnt(14)
	v_mul_f32_e32 v130, v130, v162
	v_mul_f32_e32 v131, v131, v162
	v_mul_f32_e32 v132, v132, v162
	v_mul_f32_e32 v133, v133, v162
	v_mul_f32_e32 v134, v134, v163
	v_mul_f32_e32 v135, v135, v163
	v_mul_f32_e32 v136, v136, v163
	v_mul_f32_e32 v137, v137, v163
	v_mul_f32_e32 v138, v138, v164
	v_mul_f32_e32 v139, v139, v164
	v_mul_f32_e32 v140, v140, v164
	v_mul_f32_e32 v141, v141, v164
	v_mul_f32_e32 v142, v142, v165
	v_mul_f32_e32 v143, v143, v165
	v_mul_f32_e32 v144, v144, v165
	v_mul_f32_e32 v145, v145, v165
	v_mul_f32_e32 v146, v146, v166
	v_mul_f32_e32 v147, v147, v166
	v_mul_f32_e32 v148, v148, v166
	v_mul_f32_e32 v149, v149, v166
	v_mul_f32_e32 v150, v150, v167
	v_mul_f32_e32 v151, v151, v167
	v_mul_f32_e32 v152, v152, v167
	v_mul_f32_e32 v153, v153, v167
	v_mul_f32_e32 v154, v154, v168
	v_mul_f32_e32 v155, v155, v168
	v_mul_f32_e32 v156, v156, v168
	v_mul_f32_e32 v157, v157, v168
	v_mul_f32_e32 v158, v158, v169
	v_mul_f32_e32 v159, v159, v169
	v_mul_f32_e32 v160, v160, v169
	v_mul_f32_e32 v161, v161, v169
	v_cvt_pk_bf16_f32 v214, v130, v134
	v_cvt_pk_bf16_f32 v215, v138, v142
	v_cvt_pk_bf16_f32 v216, v146, v150
	v_cvt_pk_bf16_f32 v217, v154, v158
	v_cvt_pk_bf16_f32 v218, v131, v135
	v_cvt_pk_bf16_f32 v219, v139, v143
	v_cvt_pk_bf16_f32 v220, v147, v151
	v_cvt_pk_bf16_f32 v221, v155, v159
	v_cvt_pk_bf16_f32 v222, v132, v136
	v_cvt_pk_bf16_f32 v223, v140, v144
	v_cvt_pk_bf16_f32 v224, v148, v152
	v_cvt_pk_bf16_f32 v225, v156, v160
	v_cvt_pk_bf16_f32 v226, v133, v137
	v_cvt_pk_bf16_f32 v227, v141, v145
	v_cvt_pk_bf16_f32 v228, v149, v153
	v_cvt_pk_bf16_f32 v229, v157, v161
	ds_write_b128 v75, v[214:217] offset:32768
	ds_write_b128 v75, v[218:221] offset:33024
	ds_write_b128 v75, v[222:225] offset:33280
	ds_write_b128 v75, v[226:229] offset:33536
	s_mov_b64 s[70:71], s[66:67]
	s_mul_i32 s12, s9, 0xba2f
	s_lshr_b32 s12, s12, 22
	s_mul_i32 s57, s12, 0x58
	s_sub_i32 s42, s9, s57
	s_mul_i32 s57, s12, 0x580000
	s_lshl_b32 s58, s42, 9
	s_add_i32 s57, s57, s58
	s_add_u32 s62, s2, s57
	s_addc_u32 s63, s3, 0
	s_lshl_b32 s58, s12, 9
	s_add_u32 s64, s4, s58
	s_addc_u32 s65, s5, 0
	s_cmp_gt_u32 s42, 43
	s_cselect_b32 s58, 0x80000, 0
	s_cselect_b32 s57, 44, 0
	s_sub_i32 s57, s42, s57
	s_lshl_b32 s57, s57, 20
	s_add_i32 s57, s57, s58
	s_lshl_b32 s58, s12, 8
	s_add_i32 s57, s57, s58
	s_add_u32 s66, s40, s57
	s_addc_u32 s67, s41, 0
	s_add_i32 s9, s9, 0x75
	s_nop 0
	global_load_dwordx4 v[162:165], v74, s[64:65] offset:0
	global_load_dwordx4 v[166:169], v74, s[64:65] offset:16
	global_load_dwordx4 v[130:133], v66, s[62:63] nt
	global_load_dwordx4 v[134:137], v67, s[62:63] nt
	global_load_dwordx4 v[138:141], v68, s[62:63] nt
	global_load_dwordx4 v[142:145], v69, s[62:63] nt
	global_load_dwordx4 v[146:149], v70, s[62:63] nt
	global_load_dwordx4 v[150:153], v71, s[62:63] nt
	global_load_dwordx4 v[154:157], v72, s[62:63] nt
	global_load_dwordx4 v[158:161], v73, s[62:63] nt
	s_waitcnt lgkmcnt(0)
	s_barrier
	ds_read_b128 v[102:105], v76 offset:32768
	ds_read_b128 v[106:109], v77 offset:40960
	ds_read_b128 v[110:113], v76 offset:49152
	ds_read_b128 v[114:117], v77 offset:57344
	s_waitcnt lgkmcnt(3)
	global_store_dwordx4 v79, v[102:105], s[70:71] nt
	s_waitcnt lgkmcnt(2)
	global_store_dwordx4 v80, v[106:109], s[70:71] nt
	s_waitcnt lgkmcnt(1)
	global_store_dwordx4 v81, v[110:113], s[70:71] nt
	s_waitcnt lgkmcnt(0)
	global_store_dwordx4 v82, v[114:117], s[70:71] nt
	s_waitcnt vmcnt(18)
	v_mul_f32_e32 v174, v174, v206
	v_mul_f32_e32 v175, v175, v206
	v_mul_f32_e32 v176, v176, v206
	v_mul_f32_e32 v177, v177, v206
	v_mul_f32_e32 v178, v178, v207
	v_mul_f32_e32 v179, v179, v207
	v_mul_f32_e32 v180, v180, v207
	v_mul_f32_e32 v181, v181, v207
	v_mul_f32_e32 v182, v182, v208
	v_mul_f32_e32 v183, v183, v208
	v_mul_f32_e32 v184, v184, v208
	v_mul_f32_e32 v185, v185, v208
	v_mul_f32_e32 v186, v186, v209
	v_mul_f32_e32 v187, v187, v209
	v_mul_f32_e32 v188, v188, v209
	v_mul_f32_e32 v189, v189, v209
	v_mul_f32_e32 v190, v190, v210
	v_mul_f32_e32 v191, v191, v210
	v_mul_f32_e32 v192, v192, v210
	v_mul_f32_e32 v193, v193, v210
	v_mul_f32_e32 v194, v194, v211
	v_mul_f32_e32 v195, v195, v211
	v_mul_f32_e32 v196, v196, v211
	v_mul_f32_e32 v197, v197, v211
	v_mul_f32_e32 v198, v198, v212
	v_mul_f32_e32 v199, v199, v212
	v_mul_f32_e32 v200, v200, v212
	v_mul_f32_e32 v201, v201, v212
	v_mul_f32_e32 v202, v202, v213
	v_mul_f32_e32 v203, v203, v213
	v_mul_f32_e32 v204, v204, v213
	v_mul_f32_e32 v205, v205, v213
	v_cvt_pk_bf16_f32 v214, v174, v178
	v_cvt_pk_bf16_f32 v215, v182, v186
	v_cvt_pk_bf16_f32 v216, v190, v194
	v_cvt_pk_bf16_f32 v217, v198, v202
	v_cvt_pk_bf16_f32 v218, v175, v179
	v_cvt_pk_bf16_f32 v219, v183, v187
	v_cvt_pk_bf16_f32 v220, v191, v195
	v_cvt_pk_bf16_f32 v221, v199, v203
	v_cvt_pk_bf16_f32 v222, v176, v180
	v_cvt_pk_bf16_f32 v223, v184, v188
	v_cvt_pk_bf16_f32 v224, v192, v196
	v_cvt_pk_bf16_f32 v225, v200, v204
	v_cvt_pk_bf16_f32 v226, v177, v181
	v_cvt_pk_bf16_f32 v227, v185, v189
	v_cvt_pk_bf16_f32 v228, v193, v197
	v_cvt_pk_bf16_f32 v229, v201, v205
	ds_write_b128 v75, v[214:217] offset:0
	ds_write_b128 v75, v[218:221] offset:256
	ds_write_b128 v75, v[222:225] offset:512
	ds_write_b128 v75, v[226:229] offset:768
	s_mov_b64 s[68:69], s[60:61]
	s_mul_i32 s12, s9, 0xba2f
	s_lshr_b32 s12, s12, 22
	s_mul_i32 s57, s12, 0x58
	s_sub_i32 s42, s9, s57
	s_mul_i32 s57, s12, 0x580000
	s_lshl_b32 s58, s42, 9
	s_add_i32 s57, s57, s58
	s_add_u32 s52, s2, s57
	s_addc_u32 s53, s3, 0
	s_lshl_b32 s58, s12, 9
	s_add_u32 s54, s4, s58
	s_addc_u32 s55, s5, 0
	s_cmp_gt_u32 s42, 43
	s_cselect_b32 s58, 0x80000, 0
	s_cselect_b32 s57, 44, 0
	s_sub_i32 s57, s42, s57
	s_lshl_b32 s57, s57, 20
	s_add_i32 s57, s57, s58
	s_lshl_b32 s58, s12, 8
	s_add_i32 s57, s57, s58
	s_add_u32 s60, s40, s57
	s_addc_u32 s61, s41, 0
	s_add_i32 s9, s9, 0x75
	s_nop 0
	global_load_dwordx4 v[206:209], v74, s[54:55] offset:0
	global_load_dwordx4 v[210:213], v74, s[54:55] offset:16
	global_load_dwordx4 v[174:177], v66, s[52:53] nt
	global_load_dwordx4 v[178:181], v67, s[52:53] nt
	global_load_dwordx4 v[182:185], v68, s[52:53] nt
	global_load_dwordx4 v[186:189], v69, s[52:53] nt
	global_load_dwordx4 v[190:193], v70, s[52:53] nt
	global_load_dwordx4 v[194:197], v71, s[52:53] nt
	global_load_dwordx4 v[198:201], v72, s[52:53] nt
	global_load_dwordx4 v[202:205], v73, s[52:53] nt
	s_waitcnt lgkmcnt(0)
	s_barrier
	ds_read_b128 v[50:53], v76 offset:0
	ds_read_b128 v[54:57], v77 offset:8192
	ds_read_b128 v[58:61], v76 offset:16384
	ds_read_b128 v[62:65], v77 offset:24576
	s_waitcnt lgkmcnt(3)
	global_store_dwordx4 v79, v[50:53], s[68:69] nt
	s_waitcnt lgkmcnt(2)
	global_store_dwordx4 v80, v[54:57], s[68:69] nt
	s_waitcnt lgkmcnt(1)
	global_store_dwordx4 v81, v[58:61], s[68:69] nt
	s_waitcnt lgkmcnt(0)
	global_store_dwordx4 v82, v[62:65], s[68:69] nt
	s_waitcnt vmcnt(18)
	v_mul_f32_e32 v130, v130, v162
	v_mul_f32_e32 v131, v131, v162
	v_mul_f32_e32 v132, v132, v162
	v_mul_f32_e32 v133, v133, v162
	v_mul_f32_e32 v134, v134, v163
	v_mul_f32_e32 v135, v135, v163
	v_mul_f32_e32 v136, v136, v163
	v_mul_f32_e32 v137, v137, v163
	v_mul_f32_e32 v138, v138, v164
	v_mul_f32_e32 v139, v139, v164
	v_mul_f32_e32 v140, v140, v164
	v_mul_f32_e32 v141, v141, v164
	v_mul_f32_e32 v142, v142, v165
	v_mul_f32_e32 v143, v143, v165
	v_mul_f32_e32 v144, v144, v165
	v_mul_f32_e32 v145, v145, v165
	v_mul_f32_e32 v146, v146, v166
	v_mul_f32_e32 v147, v147, v166
	v_mul_f32_e32 v148, v148, v166
	v_mul_f32_e32 v149, v149, v166
	v_mul_f32_e32 v150, v150, v167
	v_mul_f32_e32 v151, v151, v167
	v_mul_f32_e32 v152, v152, v167
	v_mul_f32_e32 v153, v153, v167
	v_mul_f32_e32 v154, v154, v168
	v_mul_f32_e32 v155, v155, v168
	v_mul_f32_e32 v156, v156, v168
	v_mul_f32_e32 v157, v157, v168
	v_mul_f32_e32 v158, v158, v169
	v_mul_f32_e32 v159, v159, v169
	v_mul_f32_e32 v160, v160, v169
	v_mul_f32_e32 v161, v161, v169
	v_cvt_pk_bf16_f32 v214, v130, v134
	v_cvt_pk_bf16_f32 v215, v138, v142
	v_cvt_pk_bf16_f32 v216, v146, v150
	v_cvt_pk_bf16_f32 v217, v154, v158
	v_cvt_pk_bf16_f32 v218, v131, v135
	v_cvt_pk_bf16_f32 v219, v139, v143
	v_cvt_pk_bf16_f32 v220, v147, v151
	v_cvt_pk_bf16_f32 v221, v155, v159
	v_cvt_pk_bf16_f32 v222, v132, v136
	v_cvt_pk_bf16_f32 v223, v140, v144
	v_cvt_pk_bf16_f32 v224, v148, v152
	v_cvt_pk_bf16_f32 v225, v156, v160
	v_cvt_pk_bf16_f32 v226, v133, v137
	v_cvt_pk_bf16_f32 v227, v141, v145
	v_cvt_pk_bf16_f32 v228, v149, v153
	v_cvt_pk_bf16_f32 v229, v157, v161
	ds_write_b128 v75, v[214:217] offset:32768
	ds_write_b128 v75, v[218:221] offset:33024
	ds_write_b128 v75, v[222:225] offset:33280
	ds_write_b128 v75, v[226:229] offset:33536
	s_mov_b64 s[70:71], s[66:67]
	s_mul_i32 s12, s9, 0xba2f
	s_lshr_b32 s12, s12, 22
	s_mul_i32 s57, s12, 0x58
	s_sub_i32 s42, s9, s57
	s_mul_i32 s57, s12, 0x580000
	s_lshl_b32 s58, s42, 9
	s_add_i32 s57, s57, s58
	s_add_u32 s62, s2, s57
	s_addc_u32 s63, s3, 0
	s_lshl_b32 s58, s12, 9
	s_add_u32 s64, s4, s58
	s_addc_u32 s65, s5, 0
	s_cmp_gt_u32 s42, 43
	s_cselect_b32 s58, 0x80000, 0
	s_cselect_b32 s57, 44, 0
	s_sub_i32 s57, s42, s57
	s_lshl_b32 s57, s57, 20
	s_add_i32 s57, s57, s58
	s_lshl_b32 s58, s12, 8
	s_add_i32 s57, s57, s58
	s_add_u32 s66, s40, s57
	s_addc_u32 s67, s41, 0
	s_add_i32 s9, s9, 0x75
	s_nop 0
	global_load_dwordx4 v[162:165], v74, s[64:65] offset:0
	global_load_dwordx4 v[166:169], v74, s[64:65] offset:16
	global_load_dwordx4 v[130:133], v66, s[62:63] nt
	global_load_dwordx4 v[134:137], v67, s[62:63] nt
	global_load_dwordx4 v[138:141], v68, s[62:63] nt
	global_load_dwordx4 v[142:145], v69, s[62:63] nt
	global_load_dwordx4 v[146:149], v70, s[62:63] nt
	global_load_dwordx4 v[150:153], v71, s[62:63] nt
	global_load_dwordx4 v[154:157], v72, s[62:63] nt
	global_load_dwordx4 v[158:161], v73, s[62:63] nt
	s_waitcnt lgkmcnt(0)
	s_barrier
	ds_read_b128 v[102:105], v76 offset:32768
	ds_read_b128 v[106:109], v77 offset:40960
	ds_read_b128 v[110:113], v76 offset:49152
	ds_read_b128 v[114:117], v77 offset:57344
	s_waitcnt lgkmcnt(3)
	global_store_dwordx4 v79, v[102:105], s[70:71] nt
	s_waitcnt lgkmcnt(2)
	global_store_dwordx4 v80, v[106:109], s[70:71] nt
	s_waitcnt lgkmcnt(1)
	global_store_dwordx4 v81, v[110:113], s[70:71] nt
	s_waitcnt lgkmcnt(0)
	global_store_dwordx4 v82, v[114:117], s[70:71] nt
	s_waitcnt vmcnt(18)
	v_mul_f32_e32 v174, v174, v206
	v_mul_f32_e32 v175, v175, v206
	v_mul_f32_e32 v176, v176, v206
	v_mul_f32_e32 v177, v177, v206
	v_mul_f32_e32 v178, v178, v207
	v_mul_f32_e32 v179, v179, v207
	v_mul_f32_e32 v180, v180, v207
	v_mul_f32_e32 v181, v181, v207
	v_mul_f32_e32 v182, v182, v208
	v_mul_f32_e32 v183, v183, v208
	v_mul_f32_e32 v184, v184, v208
	v_mul_f32_e32 v185, v185, v208
	v_mul_f32_e32 v186, v186, v209
	v_mul_f32_e32 v187, v187, v209
	v_mul_f32_e32 v188, v188, v209
	v_mul_f32_e32 v189, v189, v209
	v_mul_f32_e32 v190, v190, v210
	v_mul_f32_e32 v191, v191, v210
	v_mul_f32_e32 v192, v192, v210
	v_mul_f32_e32 v193, v193, v210
	v_mul_f32_e32 v194, v194, v211
	v_mul_f32_e32 v195, v195, v211
	v_mul_f32_e32 v196, v196, v211
	v_mul_f32_e32 v197, v197, v211
	v_mul_f32_e32 v198, v198, v212
	v_mul_f32_e32 v199, v199, v212
	v_mul_f32_e32 v200, v200, v212
	v_mul_f32_e32 v201, v201, v212
	v_mul_f32_e32 v202, v202, v213
	v_mul_f32_e32 v203, v203, v213
	v_mul_f32_e32 v204, v204, v213
	v_mul_f32_e32 v205, v205, v213
	v_cvt_pk_bf16_f32 v214, v174, v178
	v_cvt_pk_bf16_f32 v215, v182, v186
	v_cvt_pk_bf16_f32 v216, v190, v194
	v_cvt_pk_bf16_f32 v217, v198, v202
	v_cvt_pk_bf16_f32 v218, v175, v179
	v_cvt_pk_bf16_f32 v219, v183, v187
	v_cvt_pk_bf16_f32 v220, v191, v195
	v_cvt_pk_bf16_f32 v221, v199, v203
	v_cvt_pk_bf16_f32 v222, v176, v180
	v_cvt_pk_bf16_f32 v223, v184, v188
	v_cvt_pk_bf16_f32 v224, v192, v196
	v_cvt_pk_bf16_f32 v225, v200, v204
	v_cvt_pk_bf16_f32 v226, v177, v181
	v_cvt_pk_bf16_f32 v227, v185, v189
	v_cvt_pk_bf16_f32 v228, v193, v197
	v_cvt_pk_bf16_f32 v229, v201, v205
	ds_write_b128 v75, v[214:217] offset:0
	ds_write_b128 v75, v[218:221] offset:256
	ds_write_b128 v75, v[222:225] offset:512
	ds_write_b128 v75, v[226:229] offset:768
	s_mov_b64 s[68:69], s[60:61]
	s_waitcnt lgkmcnt(0)
	s_barrier
	ds_read_b128 v[50:53], v76 offset:0
	ds_read_b128 v[54:57], v77 offset:8192
	ds_read_b128 v[58:61], v76 offset:16384
	ds_read_b128 v[62:65], v77 offset:24576
	s_waitcnt lgkmcnt(3)
	global_store_dwordx4 v79, v[50:53], s[68:69] nt
	s_waitcnt lgkmcnt(2)
	global_store_dwordx4 v80, v[54:57], s[68:69] nt
	s_waitcnt lgkmcnt(1)
	global_store_dwordx4 v81, v[58:61], s[68:69] nt
	s_waitcnt lgkmcnt(0)
	global_store_dwordx4 v82, v[62:65], s[68:69] nt
	s_waitcnt vmcnt(8)
	v_mul_f32_e32 v130, v130, v162
	v_mul_f32_e32 v131, v131, v162
	v_mul_f32_e32 v132, v132, v162
	v_mul_f32_e32 v133, v133, v162
	v_mul_f32_e32 v134, v134, v163
	v_mul_f32_e32 v135, v135, v163
	v_mul_f32_e32 v136, v136, v163
	v_mul_f32_e32 v137, v137, v163
	v_mul_f32_e32 v138, v138, v164
	v_mul_f32_e32 v139, v139, v164
	v_mul_f32_e32 v140, v140, v164
	v_mul_f32_e32 v141, v141, v164
	v_mul_f32_e32 v142, v142, v165
	v_mul_f32_e32 v143, v143, v165
	v_mul_f32_e32 v144, v144, v165
	v_mul_f32_e32 v145, v145, v165
	v_mul_f32_e32 v146, v146, v166
	v_mul_f32_e32 v147, v147, v166
	v_mul_f32_e32 v148, v148, v166
	v_mul_f32_e32 v149, v149, v166
	v_mul_f32_e32 v150, v150, v167
	v_mul_f32_e32 v151, v151, v167
	v_mul_f32_e32 v152, v152, v167
	v_mul_f32_e32 v153, v153, v167
	v_mul_f32_e32 v154, v154, v168
	v_mul_f32_e32 v155, v155, v168
	v_mul_f32_e32 v156, v156, v168
	v_mul_f32_e32 v157, v157, v168
	v_mul_f32_e32 v158, v158, v169
	v_mul_f32_e32 v159, v159, v169
	v_mul_f32_e32 v160, v160, v169
	v_mul_f32_e32 v161, v161, v169
	v_cvt_pk_bf16_f32 v214, v130, v134
	v_cvt_pk_bf16_f32 v215, v138, v142
	v_cvt_pk_bf16_f32 v216, v146, v150
	v_cvt_pk_bf16_f32 v217, v154, v158
	v_cvt_pk_bf16_f32 v218, v131, v135
	v_cvt_pk_bf16_f32 v219, v139, v143
	v_cvt_pk_bf16_f32 v220, v147, v151
	v_cvt_pk_bf16_f32 v221, v155, v159
	v_cvt_pk_bf16_f32 v222, v132, v136
	v_cvt_pk_bf16_f32 v223, v140, v144
	v_cvt_pk_bf16_f32 v224, v148, v152
	v_cvt_pk_bf16_f32 v225, v156, v160
	v_cvt_pk_bf16_f32 v226, v133, v137
	v_cvt_pk_bf16_f32 v227, v141, v145
	v_cvt_pk_bf16_f32 v228, v149, v153
	v_cvt_pk_bf16_f32 v229, v157, v161
	ds_write_b128 v75, v[214:217] offset:32768
	ds_write_b128 v75, v[218:221] offset:33024
	ds_write_b128 v75, v[222:225] offset:33280
	ds_write_b128 v75, v[226:229] offset:33536
	s_mov_b64 s[70:71], s[66:67]
	s_waitcnt lgkmcnt(0)
	s_barrier
	ds_read_b128 v[102:105], v76 offset:32768
	ds_read_b128 v[106:109], v77 offset:40960
	ds_read_b128 v[110:113], v76 offset:49152
	ds_read_b128 v[114:117], v77 offset:57344
	s_waitcnt lgkmcnt(3)
	global_store_dwordx4 v79, v[102:105], s[70:71] nt
	s_waitcnt lgkmcnt(2)
	global_store_dwordx4 v80, v[106:109], s[70:71] nt
	s_waitcnt lgkmcnt(1)
	global_store_dwordx4 v81, v[110:113], s[70:71] nt
	s_waitcnt lgkmcnt(0)
	global_store_dwordx4 v82, v[114:117], s[70:71] nt
	s_waitcnt vmcnt(0)
	s_barrier
